# first layer: next layer's phase-0 rmsnorm folded into phase 6 (x_next stored and kept in accumulators, xn written after the grid barrier, phase-0 rmsnorm loop skipped in layer 2)
# speedup vs baseline: 1.0464x; 1.0159x over previous
; DI unsigned pack2(float a, float b) { fv2 v = {a, b}; return __builtin_bit_cast(unsigned, __builtin_convertvector(v, bfv2)); }
; DI void rmsnorm_rows(const float* x, const float* g, bf16_t* outb, float* outf) {
;     ...
;     for (int rr = 0; rr < 2; ++rr) {
;       const int row = it * 16 + rr * 8 + w;
;       const float rs = rsqrtf(ss[rr] * (1.f / 1024.f) + 1e-6f);
; #pragma unroll
;       for (int i = 0; i < 4; ++i) {
;         const float o0 = v[rr][i].x * rs * gg[i].x, o1 = v[rr][i].y * rs * gg[i].y, o2 = v[rr][i].z * rs * gg[i].z, o3 = v[rr][i].w * rs * gg[i].w;
;         if (outf) { *(float4*)(outf + (size_t)row * 1024 + lane * 4 + 256 * i) = make_float4(o0, o1, o2, o3); }
;         else { uint2 o; o.x = pack2(o0, o1); o.y = pack2(o2, o3); *(uint2*)(outb + (size_t)row * 1024 + lane * 4 + 256 * i) = o; }
;       }
.LBB0_19:
	s_or_b64 exec, exec, s[2:3]
	v_readlane_b32 s0, v252, 50
	v_readlane_b32 s1, v252, 51
	s_mov_b32 s4, 1
	s_mov_b64 s[8:9], -1
	s_mov_b64 s[2:3], 0
	s_and_b64 vcc, exec, s[0:1]
	s_waitcnt lgkmcnt(0)
	s_barrier
	s_cbranch_vccnz .Ltramp_1087
	s_cmp_eq_u32 s92, 2
	s_cbranch_scc0 .Lfz_no2
	v_readlane_b32 s94, v252, 6
	v_readlane_b32 s95, v252, 7
	s_load_dwordx2 s[96:97], s[94:95], 0xf0
	s_load_dwordx2 s[98:99], s[94:95], 0x8
	v_lshrrev_b32_e32 v191, 6, v201
	v_lshrrev_b32_e32 v192, 2, v191
	v_and_b32_e32 v193, 3, v191
	v_and_b32_e32 v194, 15, v201
	v_bfe_u32 v195, v201, 4, 2
	v_lshlrev_b32_e32 v190, 17, v192
	v_lshl_or_b32 v190, v194, 11, v190
	v_lshl_or_b32 v190, v193, 6, v190
	v_lshl_or_b32 v190, v195, 3, v190
	v_lshlrev_b32_e32 v198, 2, v201
	v_mov_b32_e32 v161, 0x358637bd
	s_mov_b32 s93, 0x800000
	v_lshlrev_b32_e32 v199, 7, v193
	v_lshl_or_b32 v199, v195, 4, v199
	s_waitcnt lgkmcnt(0)
	s_lshl_b32 s88, s91, 10
	s_add_u32 s98, s98, 0x1000
	s_addc_u32 s99, s99, 0
	s_add_u32 s98, s98, s88
	s_addc_u32 s99, s99, 0
	global_load_dwordx4 v[162:165], v199, s[98:99]
	global_load_dwordx4 v[166:169], v199, s[98:99] offset:64
	global_load_dwordx4 v[170:173], v199, s[98:99] offset:512
	global_load_dwordx4 v[174:177], v199, s[98:99] offset:576
	s_add_u32 s100, s96, 0xaaa4500
	s_addc_u32 s101, s97, 0
	s_lshl_b32 s88, s90, 10
	s_add_u32 s100, s100, s88
	s_addc_u32 s101, s101, 0
	v_cmp_gt_u32_e32 vcc, 0x100, v201
	s_and_saveexec_b64 s[94:95], vcc
	global_load_dword v150, v198, s[100:101]
	s_add_u32 s100, s100, 0x10000
	s_addc_u32 s101, s101, 0
	global_load_dword v151, v198, s[100:101]
	s_add_u32 s100, s100, 0x10000
	s_addc_u32 s101, s101, 0
	global_load_dword v152, v198, s[100:101]
	s_add_u32 s100, s100, 0x10000
	s_addc_u32 s101, s101, 0
	global_load_dword v153, v198, s[100:101]
	s_waitcnt vmcnt(0)
	v_add_f32_e32 v150, v150, v151
	v_add_f32_e32 v150, v150, v152
	v_add_f32_e32 v150, v150, v153
	v_fmamk_f32 v160, v150, 0x3a800000, v161
	v_mul_f32_e32 v154, 0x4b800000, v160
	v_cmp_gt_f32_e32 vcc, s93, v160
	s_nop 1
	v_cndmask_b32_e32 v160, v160, v154, vcc
	v_rsq_f32_e32 v160, v160
	s_nop 0
	v_mul_f32_e32 v154, 0x45800000, v160
	v_cndmask_b32_e32 v160, v160, v154, vcc
	v_add_u32_e32 v155, 0x20000, v198
	ds_write_b32 v155, v160
	s_mov_b64 exec, s[94:95]
	s_waitcnt vmcnt(0) lgkmcnt(0)
	s_barrier
	v_lshl_or_b32 v196, v192, 6, v194
	v_lshlrev_b32_e32 v196, 2, v196
	v_add_u32_e32 v196, 0x20000, v196
	ds_read_b32 v182, v196
	ds_read_b32 v183, v196 offset:64
	ds_read_b32 v184, v196 offset:128
	ds_read_b32 v185, v196 offset:192
	ds_read_b32 v186, v196 offset:512
	ds_read_b32 v187, v196 offset:576
	ds_read_b32 v188, v196 offset:640
	ds_read_b32 v189, v196 offset:704
	s_add_u32 s100, s96, 0x12a4500
	s_addc_u32 s101, s97, 0
	s_lshl_b32 s88, s90, 19
	s_add_u32 s100, s100, s88
	s_addc_u32 s101, s101, 0
	s_lshl_b32 s88, s91, 9
	s_add_u32 s100, s100, s88
	s_addc_u32 s101, s101, 0
	s_waitcnt lgkmcnt(0)
	s_add_u32 s94, s100, 0x0
	s_addc_u32 s95, s101, 0
	v_pk_mul_f32 v[126:127], v[126:127], v[182:183] op_sel_hi:[1,0]
	v_pk_mul_f32 v[128:129], v[128:129], v[182:183] op_sel_hi:[1,0]
	v_pk_mul_f32 v[126:127], v[162:163], v[126:127]
	v_pk_mul_f32 v[128:129], v[164:165], v[128:129]
	v_cvt_pk_bf16_f32 v126, v126, v127
	v_cvt_pk_bf16_f32 v127, v128, v129
	global_store_dwordx2 v190, v[126:127], s[94:95]
	v_pk_mul_f32 v[122:123], v[122:123], v[182:183] op_sel_hi:[1,0]
	v_pk_mul_f32 v[124:125], v[124:125], v[182:183] op_sel_hi:[1,0]
	v_pk_mul_f32 v[122:123], v[166:167], v[122:123]
	v_pk_mul_f32 v[124:125], v[168:169], v[124:125]
	v_cvt_pk_bf16_f32 v122, v122, v123
	v_cvt_pk_bf16_f32 v123, v124, v125
	global_store_dwordx2 v190, v[122:123], s[94:95] offset:32
	v_pk_mul_f32 v[110:111], v[110:111], v[182:183] op_sel_hi:[1,0]
	v_pk_mul_f32 v[112:113], v[112:113], v[182:183] op_sel_hi:[1,0]
	v_pk_mul_f32 v[110:111], v[170:171], v[110:111]
	v_pk_mul_f32 v[112:113], v[172:173], v[112:113]
	v_cvt_pk_bf16_f32 v110, v110, v111
	v_cvt_pk_bf16_f32 v111, v112, v113
	global_store_dwordx2 v190, v[110:111], s[94:95] offset:256
	v_pk_mul_f32 v[106:107], v[106:107], v[182:183] op_sel_hi:[1,0]
	v_pk_mul_f32 v[108:109], v[108:109], v[182:183] op_sel_hi:[1,0]
	v_pk_mul_f32 v[106:107], v[174:175], v[106:107]
	v_pk_mul_f32 v[108:109], v[176:177], v[108:109]
	v_cvt_pk_bf16_f32 v106, v106, v107
	v_cvt_pk_bf16_f32 v107, v108, v109
	global_store_dwordx2 v190, v[106:107], s[94:95] offset:288
	s_add_u32 s94, s100, 0x8000
	s_addc_u32 s95, s101, 0
	v_pk_mul_f32 v[118:119], v[118:119], v[182:183] op_sel:[0,1] op_sel_hi:[1,1]
	v_pk_mul_f32 v[120:121], v[120:121], v[182:183] op_sel:[0,1] op_sel_hi:[1,1]
	v_pk_mul_f32 v[118:119], v[162:163], v[118:119]
	v_pk_mul_f32 v[120:121], v[164:165], v[120:121]
	v_cvt_pk_bf16_f32 v118, v118, v119
	v_cvt_pk_bf16_f32 v119, v120, v121
	global_store_dwordx2 v190, v[118:119], s[94:95]
	v_pk_mul_f32 v[114:115], v[114:115], v[182:183] op_sel:[0,1] op_sel_hi:[1,1]
	v_pk_mul_f32 v[116:117], v[116:117], v[182:183] op_sel:[0,1] op_sel_hi:[1,1]
	v_pk_mul_f32 v[114:115], v[166:167], v[114:115]
	v_pk_mul_f32 v[116:117], v[168:169], v[116:117]
	v_cvt_pk_bf16_f32 v114, v114, v115
	v_cvt_pk_bf16_f32 v115, v116, v117
	global_store_dwordx2 v190, v[114:115], s[94:95] offset:32
	v_pk_mul_f32 v[102:103], v[102:103], v[182:183] op_sel:[0,1] op_sel_hi:[1,1]
	v_pk_mul_f32 v[104:105], v[104:105], v[182:183] op_sel:[0,1] op_sel_hi:[1,1]
	v_pk_mul_f32 v[102:103], v[170:171], v[102:103]
	v_pk_mul_f32 v[104:105], v[172:173], v[104:105]
	v_cvt_pk_bf16_f32 v102, v102, v103
	v_cvt_pk_bf16_f32 v103, v104, v105
	global_store_dwordx2 v190, v[102:103], s[94:95] offset:256
; DI unsigned pack2(float a, float b) { fv2 v = {a, b}; return __builtin_bit_cast(unsigned, __builtin_convertvector(v, bfv2)); }
; DI void rmsnorm_rows(const float* x, const float* g, bf16_t* outb, float* outf) {
;     ...
;       for (int i = 0; i < 4; ++i) {
;         const float o0 = v[rr][i].x * rs * gg[i].x, o1 = v[rr][i].y * rs * gg[i].y, o2 = v[rr][i].z * rs * gg[i].z, o3 = v[rr][i].w * rs * gg[i].w;
;         if (outf) { *(float4*)(outf + (size_t)row * 1024 + lane * 4 + 256 * i) = make_float4(o0, o1, o2, o3); }
;         else { uint2 o; o.x = pack2(o0, o1); o.y = pack2(o2, o3); *(uint2*)(outb + (size_t)row * 1024 + lane * 4 + 256 * i) = o; }
;       }
	v_pk_mul_f32 v[98:99], v[98:99], v[182:183] op_sel:[0,1] op_sel_hi:[1,1]
	v_pk_mul_f32 v[100:101], v[100:101], v[182:183] op_sel:[0,1] op_sel_hi:[1,1]
	v_pk_mul_f32 v[98:99], v[174:175], v[98:99]
	v_pk_mul_f32 v[100:101], v[176:177], v[100:101]
	v_cvt_pk_bf16_f32 v98, v98, v99
	v_cvt_pk_bf16_f32 v99, v100, v101
	global_store_dwordx2 v190, v[98:99], s[94:95] offset:288
	s_add_u32 s94, s100, 0x10000
	s_addc_u32 s95, s101, 0
	v_pk_mul_f32 v[94:95], v[94:95], v[184:185] op_sel_hi:[1,0]
	v_pk_mul_f32 v[96:97], v[96:97], v[184:185] op_sel_hi:[1,0]
	v_pk_mul_f32 v[94:95], v[162:163], v[94:95]
	v_pk_mul_f32 v[96:97], v[164:165], v[96:97]
	v_cvt_pk_bf16_f32 v94, v94, v95
	v_cvt_pk_bf16_f32 v95, v96, v97
	global_store_dwordx2 v190, v[94:95], s[94:95]
	v_pk_mul_f32 v[90:91], v[90:91], v[184:185] op_sel_hi:[1,0]
	v_pk_mul_f32 v[92:93], v[92:93], v[184:185] op_sel_hi:[1,0]
	v_pk_mul_f32 v[90:91], v[166:167], v[90:91]
	v_pk_mul_f32 v[92:93], v[168:169], v[92:93]
	v_cvt_pk_bf16_f32 v90, v90, v91
	v_cvt_pk_bf16_f32 v91, v92, v93
	global_store_dwordx2 v190, v[90:91], s[94:95] offset:32
	v_pk_mul_f32 v[78:79], v[78:79], v[184:185] op_sel_hi:[1,0]
	v_pk_mul_f32 v[80:81], v[80:81], v[184:185] op_sel_hi:[1,0]
	v_pk_mul_f32 v[78:79], v[170:171], v[78:79]
	v_pk_mul_f32 v[80:81], v[172:173], v[80:81]
	v_cvt_pk_bf16_f32 v78, v78, v79
	v_cvt_pk_bf16_f32 v79, v80, v81
	global_store_dwordx2 v190, v[78:79], s[94:95] offset:256
	v_pk_mul_f32 v[74:75], v[74:75], v[184:185] op_sel_hi:[1,0]
	v_pk_mul_f32 v[76:77], v[76:77], v[184:185] op_sel_hi:[1,0]
	v_pk_mul_f32 v[74:75], v[174:175], v[74:75]
	v_pk_mul_f32 v[76:77], v[176:177], v[76:77]
	v_cvt_pk_bf16_f32 v74, v74, v75
	v_cvt_pk_bf16_f32 v75, v76, v77
	global_store_dwordx2 v190, v[74:75], s[94:95] offset:288
	s_add_u32 s94, s100, 0x18000
	s_addc_u32 s95, s101, 0
	v_pk_mul_f32 v[86:87], v[86:87], v[184:185] op_sel:[0,1] op_sel_hi:[1,1]
	v_pk_mul_f32 v[88:89], v[88:89], v[184:185] op_sel:[0,1] op_sel_hi:[1,1]
	v_pk_mul_f32 v[86:87], v[162:163], v[86:87]
	v_pk_mul_f32 v[88:89], v[164:165], v[88:89]
	v_cvt_pk_bf16_f32 v86, v86, v87
	v_cvt_pk_bf16_f32 v87, v88, v89
	global_store_dwordx2 v190, v[86:87], s[94:95]
	v_pk_mul_f32 v[82:83], v[82:83], v[184:185] op_sel:[0,1] op_sel_hi:[1,1]
	v_pk_mul_f32 v[84:85], v[84:85], v[184:185] op_sel:[0,1] op_sel_hi:[1,1]
	v_pk_mul_f32 v[82:83], v[166:167], v[82:83]
	v_pk_mul_f32 v[84:85], v[168:169], v[84:85]
	v_cvt_pk_bf16_f32 v82, v82, v83
	v_cvt_pk_bf16_f32 v83, v84, v85
	global_store_dwordx2 v190, v[82:83], s[94:95] offset:32
	v_pk_mul_f32 v[70:71], v[70:71], v[184:185] op_sel:[0,1] op_sel_hi:[1,1]
	v_pk_mul_f32 v[72:73], v[72:73], v[184:185] op_sel:[0,1] op_sel_hi:[1,1]
	v_pk_mul_f32 v[70:71], v[170:171], v[70:71]
	v_pk_mul_f32 v[72:73], v[172:173], v[72:73]
	v_cvt_pk_bf16_f32 v70, v70, v71
	v_cvt_pk_bf16_f32 v71, v72, v73
	global_store_dwordx2 v190, v[70:71], s[94:95] offset:256
	v_pk_mul_f32 v[66:67], v[66:67], v[184:185] op_sel:[0,1] op_sel_hi:[1,1]
	v_pk_mul_f32 v[68:69], v[68:69], v[184:185] op_sel:[0,1] op_sel_hi:[1,1]
	v_pk_mul_f32 v[66:67], v[174:175], v[66:67]
	v_pk_mul_f32 v[68:69], v[176:177], v[68:69]
	v_cvt_pk_bf16_f32 v66, v66, v67
	v_cvt_pk_bf16_f32 v67, v68, v69
	global_store_dwordx2 v190, v[66:67], s[94:95] offset:288
	s_add_u32 s94, s100, 0x40000
	s_addc_u32 s95, s101, 0
	v_pk_mul_f32 v[62:63], v[62:63], v[186:187] op_sel_hi:[1,0]
	v_pk_mul_f32 v[64:65], v[64:65], v[186:187] op_sel_hi:[1,0]
	v_pk_mul_f32 v[62:63], v[162:163], v[62:63]
	v_pk_mul_f32 v[64:65], v[164:165], v[64:65]
	v_cvt_pk_bf16_f32 v62, v62, v63
	v_cvt_pk_bf16_f32 v63, v64, v65
	global_store_dwordx2 v190, v[62:63], s[94:95]
	v_pk_mul_f32 v[58:59], v[58:59], v[186:187] op_sel_hi:[1,0]
	v_pk_mul_f32 v[60:61], v[60:61], v[186:187] op_sel_hi:[1,0]
	v_pk_mul_f32 v[58:59], v[166:167], v[58:59]
	v_pk_mul_f32 v[60:61], v[168:169], v[60:61]
	v_cvt_pk_bf16_f32 v58, v58, v59
	v_cvt_pk_bf16_f32 v59, v60, v61
	global_store_dwordx2 v190, v[58:59], s[94:95] offset:32
	v_pk_mul_f32 v[46:47], v[46:47], v[186:187] op_sel_hi:[1,0]
	v_pk_mul_f32 v[48:49], v[48:49], v[186:187] op_sel_hi:[1,0]
	v_pk_mul_f32 v[46:47], v[170:171], v[46:47]
	v_pk_mul_f32 v[48:49], v[172:173], v[48:49]
	v_cvt_pk_bf16_f32 v46, v46, v47
	v_cvt_pk_bf16_f32 v47, v48, v49
	global_store_dwordx2 v190, v[46:47], s[94:95] offset:256
	v_pk_mul_f32 v[42:43], v[42:43], v[186:187] op_sel_hi:[1,0]
	v_pk_mul_f32 v[44:45], v[44:45], v[186:187] op_sel_hi:[1,0]
	v_pk_mul_f32 v[42:43], v[174:175], v[42:43]
	v_pk_mul_f32 v[44:45], v[176:177], v[44:45]
	v_cvt_pk_bf16_f32 v42, v42, v43
	v_cvt_pk_bf16_f32 v43, v44, v45
	global_store_dwordx2 v190, v[42:43], s[94:95] offset:288
	s_add_u32 s94, s100, 0x48000
	s_addc_u32 s95, s101, 0
	v_pk_mul_f32 v[54:55], v[54:55], v[186:187] op_sel:[0,1] op_sel_hi:[1,1]
	v_pk_mul_f32 v[56:57], v[56:57], v[186:187] op_sel:[0,1] op_sel_hi:[1,1]
	v_pk_mul_f32 v[54:55], v[162:163], v[54:55]
	v_pk_mul_f32 v[56:57], v[164:165], v[56:57]
	v_cvt_pk_bf16_f32 v54, v54, v55
	v_cvt_pk_bf16_f32 v55, v56, v57
	global_store_dwordx2 v190, v[54:55], s[94:95]
; DI unsigned pack2(float a, float b) { fv2 v = {a, b}; return __builtin_bit_cast(unsigned, __builtin_convertvector(v, bfv2)); }
; DI int tidx() { int t = threadIdx.x; asm volatile("" : "+v"(t)); return t; }
; DI int bidx() { int b = blockIdx.x; asm volatile("" : "+s"(b)); return b; }
; DI void rmsnorm_rows(const float* x, const float* g, bf16_t* outb, float* outf) {
;     ...
;       for (int i = 0; i < 4; ++i) {
;         const float o0 = v[rr][i].x * rs * gg[i].x, o1 = v[rr][i].y * rs * gg[i].y, o2 = v[rr][i].z * rs * gg[i].z, o3 = v[rr][i].w * rs * gg[i].w;
;         if (outf) { *(float4*)(outf + (size_t)row * 1024 + lane * 4 + 256 * i) = make_float4(o0, o1, o2, o3); }
;         else { uint2 o; o.x = pack2(o0, o1); o.y = pack2(o2, o3); *(uint2*)(outb + (size_t)row * 1024 + lane * 4 + 256 * i) = o; }
;       }
; DI void phase0(const Params& p, int l, char* smraw) {
;   const int half = tidx() >> 8, ltid = tidx() & 255;
;   float* tile = (float*)(smraw + half * 17408);
;   {
;     int id0 = bidx() * 2;
;     TrTile cur = tr_find(p, l, id0 + half);
	v_pk_mul_f32 v[50:51], v[50:51], v[186:187] op_sel:[0,1] op_sel_hi:[1,1]
	v_pk_mul_f32 v[52:53], v[52:53], v[186:187] op_sel:[0,1] op_sel_hi:[1,1]
	v_pk_mul_f32 v[50:51], v[166:167], v[50:51]
	v_pk_mul_f32 v[52:53], v[168:169], v[52:53]
	v_cvt_pk_bf16_f32 v50, v50, v51
	v_cvt_pk_bf16_f32 v51, v52, v53
	global_store_dwordx2 v190, v[50:51], s[94:95] offset:32
	v_pk_mul_f32 v[38:39], v[38:39], v[186:187] op_sel:[0,1] op_sel_hi:[1,1]
	v_pk_mul_f32 v[40:41], v[40:41], v[186:187] op_sel:[0,1] op_sel_hi:[1,1]
	v_pk_mul_f32 v[38:39], v[170:171], v[38:39]
	v_pk_mul_f32 v[40:41], v[172:173], v[40:41]
	v_cvt_pk_bf16_f32 v38, v38, v39
	v_cvt_pk_bf16_f32 v39, v40, v41
	global_store_dwordx2 v190, v[38:39], s[94:95] offset:256
	v_pk_mul_f32 v[34:35], v[34:35], v[186:187] op_sel:[0,1] op_sel_hi:[1,1]
	v_pk_mul_f32 v[36:37], v[36:37], v[186:187] op_sel:[0,1] op_sel_hi:[1,1]
	v_pk_mul_f32 v[34:35], v[174:175], v[34:35]
	v_pk_mul_f32 v[36:37], v[176:177], v[36:37]
	v_cvt_pk_bf16_f32 v34, v34, v35
	v_cvt_pk_bf16_f32 v35, v36, v37
	global_store_dwordx2 v190, v[34:35], s[94:95] offset:288
	s_add_u32 s94, s100, 0x50000
	s_addc_u32 s95, s101, 0
	v_pk_mul_f32 v[30:31], v[30:31], v[188:189] op_sel_hi:[1,0]
	v_pk_mul_f32 v[32:33], v[32:33], v[188:189] op_sel_hi:[1,0]
	v_pk_mul_f32 v[30:31], v[162:163], v[30:31]
	v_pk_mul_f32 v[32:33], v[164:165], v[32:33]
	v_cvt_pk_bf16_f32 v30, v30, v31
	v_cvt_pk_bf16_f32 v31, v32, v33
	global_store_dwordx2 v190, v[30:31], s[94:95]
	v_pk_mul_f32 v[26:27], v[26:27], v[188:189] op_sel_hi:[1,0]
	v_pk_mul_f32 v[28:29], v[28:29], v[188:189] op_sel_hi:[1,0]
	v_pk_mul_f32 v[26:27], v[166:167], v[26:27]
	v_pk_mul_f32 v[28:29], v[168:169], v[28:29]
	v_cvt_pk_bf16_f32 v26, v26, v27
	v_cvt_pk_bf16_f32 v27, v28, v29
	global_store_dwordx2 v190, v[26:27], s[94:95] offset:32
	v_pk_mul_f32 v[134:135], v[134:135], v[188:189] op_sel_hi:[1,0]
	v_pk_mul_f32 v[136:137], v[136:137], v[188:189] op_sel_hi:[1,0]
	v_pk_mul_f32 v[134:135], v[170:171], v[134:135]
	v_pk_mul_f32 v[136:137], v[172:173], v[136:137]
	v_cvt_pk_bf16_f32 v134, v134, v135
	v_cvt_pk_bf16_f32 v135, v136, v137
	global_store_dwordx2 v190, v[134:135], s[94:95] offset:256
	v_pk_mul_f32 v[138:139], v[138:139], v[188:189] op_sel_hi:[1,0]
	v_pk_mul_f32 v[140:141], v[140:141], v[188:189] op_sel_hi:[1,0]
	v_pk_mul_f32 v[138:139], v[174:175], v[138:139]
	v_pk_mul_f32 v[140:141], v[176:177], v[140:141]
	v_cvt_pk_bf16_f32 v138, v138, v139
	v_cvt_pk_bf16_f32 v139, v140, v141
	global_store_dwordx2 v190, v[138:139], s[94:95] offset:288
	s_add_u32 s94, s100, 0x58000
	s_addc_u32 s95, s101, 0
	v_pk_mul_f32 v[22:23], v[22:23], v[188:189] op_sel:[0,1] op_sel_hi:[1,1]
	v_pk_mul_f32 v[24:25], v[24:25], v[188:189] op_sel:[0,1] op_sel_hi:[1,1]
	v_pk_mul_f32 v[22:23], v[162:163], v[22:23]
	v_pk_mul_f32 v[24:25], v[164:165], v[24:25]
	v_cvt_pk_bf16_f32 v22, v22, v23
	v_cvt_pk_bf16_f32 v23, v24, v25
	global_store_dwordx2 v190, v[22:23], s[94:95]
	v_pk_mul_f32 v[130:131], v[130:131], v[188:189] op_sel:[0,1] op_sel_hi:[1,1]
	v_pk_mul_f32 v[132:133], v[132:133], v[188:189] op_sel:[0,1] op_sel_hi:[1,1]
	v_pk_mul_f32 v[130:131], v[166:167], v[130:131]
	v_pk_mul_f32 v[132:133], v[168:169], v[132:133]
	v_cvt_pk_bf16_f32 v130, v130, v131
	v_cvt_pk_bf16_f32 v131, v132, v133
	global_store_dwordx2 v190, v[130:131], s[94:95] offset:32
	v_pk_mul_f32 v[142:143], v[142:143], v[188:189] op_sel:[0,1] op_sel_hi:[1,1]
	v_pk_mul_f32 v[144:145], v[144:145], v[188:189] op_sel:[0,1] op_sel_hi:[1,1]
	v_pk_mul_f32 v[142:143], v[170:171], v[142:143]
	v_pk_mul_f32 v[144:145], v[172:173], v[144:145]
	v_cvt_pk_bf16_f32 v142, v142, v143
	v_cvt_pk_bf16_f32 v143, v144, v145
	global_store_dwordx2 v190, v[142:143], s[94:95] offset:256
	v_pk_mul_f32 v[146:147], v[146:147], v[188:189] op_sel:[0,1] op_sel_hi:[1,1]
	v_pk_mul_f32 v[148:149], v[148:149], v[188:189] op_sel:[0,1] op_sel_hi:[1,1]
	v_pk_mul_f32 v[146:147], v[174:175], v[146:147]
	v_pk_mul_f32 v[148:149], v[176:177], v[148:149]
	v_cvt_pk_bf16_f32 v146, v146, v147
	v_cvt_pk_bf16_f32 v147, v148, v149
	global_store_dwordx2 v190, v[146:147], s[94:95] offset:288
.Lfz_no2:
.LBB0_20:
	s_xor_b64 s[0:1], s[2:3], -1
	v_writelane_b32 v252, s0, 50
	v_mov_b32_e32 v0, v201
	v_mov_b32_e32 v24, v201
	v_writelane_b32 v252, s1, 51
	s_movk_i32 s0, 0x94c
	v_readlane_b32 s22, v252, 4
	v_ashrrev_i32_e32 v36, 8, v0
	s_lshl_b32 s60, s22, 1
	v_add_u32_e32 v0, s60, v36
	v_cmp_gt_i32_e64 s[42:43], s0, v0
	v_readlane_b32 s0, v252, 6
	v_readlane_b32 s1, v252, 7
	s_mov_b64 s[2:3], s[0:1]
	s_mov_b64 s[2:3], s[0:1]
	s_mov_b32 s1, s89
	s_mul_i32 s0, s4, 0x6a6000
	s_xor_b64 s[12:13], s[8:9], -1
	v_cndmask_b32_e64 v0, 0, v0, s[42:43]
	s_lshl_b32 s2, s4, 14
	s_mov_b32 s3, s89
	s_lshl_b32 s34, s4, 13
	s_mov_b32 s35, s89
	s_lshl_b32 s36, s4, 18
	s_mov_b32 s37, s89
	s_lshl_b32 s38, s4, 20
	s_mov_b32 s39, s89
	s_mov_b32 s68, s4
	s_lshl_b32 s40, s4, 19
	s_mov_b32 s41, s89
	s_mov_b64 s[44:45], 0
	v_writelane_b32 v252, s0, 52
	s_mov_b32 s23, s1
	s_nop 0
	v_writelane_b32 v252, s1, 53
	s_branch .LBB0_22

; DI int bidx() { int b = blockIdx.x; asm volatile("" : "+s"(b)); return b; }
; DI const float* IN(int i) { return *(const float* const __attribute__((address_space(4)))*)(KA() + 8 * i); }
; DI float* OUTP() { return *(float* const __attribute__((address_space(4)))*)(KA() + 8 * 29); }
; DI char* WS(const Params&) { return *(char* const __attribute__((address_space(4)))*)(KA() + 8 * 30); }
; DI void rmsnorm_rows(const float* x, const float* g, bf16_t* outb, float* outf) {
;     ...
;   for (int it = bidx(); it < NTOK / 16; it += gridDim.x) {
;     float4 v[2][4]; float ss[2] = {0.f, 0.f};
; #pragma unroll
;     for (int rr = 0; rr < 2; ++rr) {
;       const float* xr = x + (size_t)(it * 16 + rr * 8 + w) * 1024;
; #pragma unroll
;       for (int i = 0; i < 4; ++i) v[rr][i] = *(const float4*)(xr + lane * 4 + 256 * i);
;     }
;     float4 gg[4];
; #pragma unroll
;     for (int i = 0; i < 4; ++i) gg[i] = *(const float4*)(g + lane * 4 + 256 * i);
; DI void phase0(const Params& p, int l, char* smraw) {
;     ...
;   const float* xin = (l == 0) ? IN(0) : OUTP();
;   rmsnorm_rows(xin, IN(1) + l * 1024, (bf16_t*)(WS(p) + O_XN), nullptr);
.LBB0_145:
	v_readlane_b32 s6, v252, 6
	v_readlane_b32 s7, v252, 7
	s_mov_b64 s[4:5], s[6:7]
	v_mov_b32_e32 v0, v201
	s_waitcnt vmcnt(0)
	v_mov_b32_e32 v2, v201
	v_readlane_b32 s20, v252, 4
	s_cmp_eq_u32 s68, 1
	s_cbranch_scc1 .LBB0_148
	s_cmpk_gt_i32 s20, 0x3ff
	s_cbranch_scc1 .LBB0_148
	s_load_dwordx2 s[2:3], s[2:3], 0x0
	s_nop 0
	s_load_dwordx2 s[4:5], s[4:5], 0x8
	s_nop 0
	s_load_dwordx2 s[6:7], s[6:7], 0xf0
	v_readlane_b32 s0, v252, 52
	v_readlane_b32 s1, v252, 53
	s_mov_b32 s11, s1
	s_lshl_b32 s10, s68, 10
	s_lshl_b64 s[22:23], s[10:11], 2
	v_lshlrev_b32_e32 v0, 2, v0
	v_ashrrev_i32_e32 v4, 6, v2
	s_waitcnt lgkmcnt(0)
	s_add_u32 s4, s4, s22
	v_and_b32_e32 v2, 0xfc, v0
	s_addc_u32 s5, s5, s23
	v_lshlrev_b32_e32 v0, 2, v2
	v_writelane_b32 v252, s0, 52
	v_lshl_add_u64 v[50:51], s[2:3], 0, v[0:1]
	v_lshl_add_u64 v[52:53], s[4:5], 0, v[0:1]
	v_lshlrev_b32_e32 v0, 1, v2
	v_writelane_b32 v252, s1, 53
	v_lshl_add_u64 v[2:3], s[6:7], 0, v[0:1]
	s_mov_b64 s[2:3], 0x12a4500
	v_lshl_add_u64 v[54:55], v[2:3], 0, s[2:3]
	v_readlane_b32 s2, v252, 6
	v_readlane_b32 s3, v252, 7
	s_load_dwordx2 s[0:1], s[2:3], 0xf8
	v_lshl_add_u32 v56, s20, 4, v4
	s_waitcnt lgkmcnt(0)
	v_readlane_b32 s1, v252, 45
	s_mov_b32 s3, 0x800000

; #define PG8_STAGE(bufoff, gbase, voff) do { _Pragma("unroll") for (int _i = 0; _i < 2; ++_i) \
;         __builtin_amdgcn_global_load_lds((const unsigned*)((const char*)(gbase) + (voff)[_i]), (LAS unsigned*)(lds + (bufoff) + ldsw + _i * 8192), 16, 0, 0); } while (0)
; #define PG8_LDA(dst, b, h) do { _Pragma("unroll") for (int m = 0; m < 4; ++m) _Pragma("unroll") for (int k = 0; k < 2; ++k) dst[m][k] = *(const LAS bf16x8*)(lds + PG8_SA(b, h) + aoff + m * 2048 + k * 1024); } while (0)
; #define PG8_LDB(dst, b, h) do { _Pragma("unroll") for (int n = 0; n < 2; ++n) _Pragma("unroll") for (int k = 0; k < 2; ++k) dst[n][k] = *(const LAS bf16x8*)(lds + PG8_SB(b, h) + boff + n * 2048 + k * 1024); } while (0)
; #define PG8_MMA(ai, bj, At, Bt) do { __builtin_amdgcn_s_setprio(1); _Pragma("unroll") for (int m = 0; m < 4; ++m) _Pragma("unroll") for (int n = 0; n < 2; ++n) _Pragma("unroll") for (int k = 0; k < 2; ++k) \
;         acc[ai][bj][m][n] = __builtin_amdgcn_mfma_f32_16x16x32_bf16(Bt[n][k], At[m][k], acc[ai][bj][m][n], 0, 0, 0); __builtin_amdgcn_s_setprio(0); } while (0)
; #define PG8_WAIT_V(n) asm volatile("s_waitcnt vmcnt(" #n ")" ::: "memory")
; #define PG8_WAIT_L(n) asm volatile("s_waitcnt lgkmcnt(" #n ")" ::: "memory")
; #define PG8_BAR __builtin_amdgcn_s_barrier()
; #define PG8_SCHED __builtin_amdgcn_sched_barrier(0)
; #define PG8_LDA(dst, b, h) do { _Pragma("unroll") for (int m = 0; m < 4; ++m) _Pragma("unroll") for (int k = 0; k < 2; ++k) dst[m][k] = *(const LAS bf16x8*)(lds + PG8_SA(b, h) + aoff + m * 2048 + k * 1024); } while (0)
; #define PG8_WAIT_V(n) asm volatile("s_waitcnt vmcnt(" #n ")" ::: "memory")
; template <class Epi, class Sched>
; DI void gemm_phase(LAS unsigned char* lds, const Gemm g, const Sched& S, const Epi& E) {
;     ...
;             PG8_LDB(B0, 0, 0); PG8_SCHED; PG8_LDA(At, 0, 0); PG8_STAGE(PG8_SA(1, 1), a1 + hstepA, voffA);
;             PG8_WAIT_L(8); PG8_BAR; PG8_WAIT_L(0); PG8_MMA(0, 0, At, B0); PG8_BAR; PG8_SCHED;
;             PG8_LDB(B1, 0, 1); PG8_STAGE(PG8_SB(0, 0), b2, voffB);
;             PG8_BAR; PG8_WAIT_L(0); PG8_MMA(0, 1, At, B1); PG8_BAR;
;             PG8_LDA(At, 0, 1); PG8_STAGE(PG8_SA(0, 0), a2, voffA);
;             PG8_BAR; PG8_WAIT_L(0); PG8_MMA(1, 0, At, B0); PG8_BAR; PG8_SCHED;
;             PG8_STAGE(PG8_SB(0, 1), b2 + hstepB, voffB);
;             PG8_WAIT_V(6); PG8_BAR; PG8_MMA(1, 1, At, B1); PG8_BAR;
.LBB0_1039:
	s_add_u32 s0, s42, 0xfffc0080
	s_addc_u32 s1, s43, -1
	s_add_i32 s11, 0, 0x10000
	s_cmp_eq_u32 s60, 12
	s_cselect_b32 s47, s6, s1
	s_cselect_b32 s46, s7, s0
	s_cselect_b32 s45, s9, s59
	s_cselect_b32 s44, s13, s58
	v_lshl_add_u64 v[188:189], s[42:43], 0, v[134:135]
	s_add_i32 m0, s51, 0xc000
	ds_read_b128 v[156:159], v147
	ds_read_b128 v[160:163], v147 offset:1024
	ds_read_b128 v[164:167], v147 offset:2048
	ds_read_b128 v[168:171], v147 offset:3072
	ds_read_b128 v[172:175], v147 offset:4096
	ds_read_b128 v[176:179], v147 offset:5120
	ds_read_b128 v[180:183], v147 offset:6144
	ds_read_b128 v[184:187], v147 offset:7168
	global_load_lds_dwordx4 v[188:189], off
	v_lshl_add_u64 v[188:189], s[42:43], 0, v[132:133]
	s_add_i32 m0, s51, 0xe000
	s_nop 0
	global_load_lds_dwordx4 v[188:189], off
	s_waitcnt lgkmcnt(8)
	s_barrier
	s_waitcnt lgkmcnt(0)
	s_setprio 1
	s_waitcnt lgkmcnt(0)
	v_mfma_f32_16x16x32_bf16 v[126:129], v[136:139], v[156:159], v[126:129]
	v_mfma_f32_16x16x32_bf16 v[122:125], v[148:151], v[156:159], v[122:125]
	v_mfma_f32_16x16x32_bf16 v[118:121], v[136:139], v[164:167], v[118:121]
	v_mfma_f32_16x16x32_bf16 v[114:117], v[148:151], v[164:167], v[114:117]
	v_mfma_f32_16x16x32_bf16 v[94:97], v[136:139], v[172:175], v[94:97]
	v_mfma_f32_16x16x32_bf16 v[90:93], v[148:151], v[172:175], v[90:93]
	v_mfma_f32_16x16x32_bf16 v[86:89], v[136:139], v[180:183], v[86:89]
	v_mfma_f32_16x16x32_bf16 v[82:85], v[148:151], v[180:183], v[82:85]
	v_mfma_f32_16x16x32_bf16 v[126:129], v[140:143], v[160:163], v[126:129]
	v_mfma_f32_16x16x32_bf16 v[122:125], v[152:155], v[160:163], v[122:125]
	v_mfma_f32_16x16x32_bf16 v[118:121], v[140:143], v[168:171], v[118:121]
	v_mfma_f32_16x16x32_bf16 v[114:117], v[152:155], v[168:171], v[114:117]
	v_mfma_f32_16x16x32_bf16 v[94:97], v[140:143], v[176:179], v[94:97]
	v_mfma_f32_16x16x32_bf16 v[90:93], v[152:155], v[176:179], v[90:93]
	v_mfma_f32_16x16x32_bf16 v[86:89], v[140:143], v[184:187], v[86:89]
	v_mfma_f32_16x16x32_bf16 v[82:85], v[152:155], v[184:187], v[82:85]
	s_setprio 0
	s_barrier
	s_add_i32 s61, 0, 0x14000
	s_add_i32 s0, s11, s50
	v_add_u32_e32 v210, s61, v145
	v_lshl_add_u64 v[214:215], s[44:45], 0, v[0:1]
	s_mov_b32 m0, s0
	ds_read_b128 v[188:191], v210
	ds_read_b128 v[192:195], v210 offset:1024
	ds_read_b128 v[196:199], v210 offset:2048
	ds_read_b128 v[210:213], v210 offset:3072
	global_load_lds_dwordx4 v[214:215], off
	v_lshl_add_u64 v[216:217], s[44:45], 0, v[130:131]
	s_add_i32 m0, s0, 0x2000
	s_nop 0
	global_load_lds_dwordx4 v[216:217], off
	s_barrier
	s_waitcnt lgkmcnt(0)
	s_setprio 1
	s_waitcnt lgkmcnt(0)
	v_mfma_f32_16x16x32_bf16 v[110:113], v[188:191], v[156:159], v[110:113]
	v_mfma_f32_16x16x32_bf16 v[106:109], v[196:199], v[156:159], v[106:109]
	v_mfma_f32_16x16x32_bf16 v[102:105], v[188:191], v[164:167], v[102:105]
	v_mfma_f32_16x16x32_bf16 v[98:101], v[196:199], v[164:167], v[98:101]
	v_mfma_f32_16x16x32_bf16 v[78:81], v[188:191], v[172:175], v[78:81]
	v_mfma_f32_16x16x32_bf16 v[74:77], v[196:199], v[172:175], v[74:77]
	v_mfma_f32_16x16x32_bf16 v[70:73], v[188:191], v[180:183], v[70:73]
	v_mfma_f32_16x16x32_bf16 v[66:69], v[196:199], v[180:183], v[66:69]
	v_mfma_f32_16x16x32_bf16 v[110:113], v[192:195], v[160:163], v[110:113]
	v_mfma_f32_16x16x32_bf16 v[106:109], v[210:213], v[160:163], v[106:109]
	v_mfma_f32_16x16x32_bf16 v[102:105], v[192:195], v[168:171], v[102:105]
	v_mfma_f32_16x16x32_bf16 v[98:101], v[210:213], v[168:171], v[98:101]
	v_mfma_f32_16x16x32_bf16 v[78:81], v[192:195], v[176:179], v[78:81]
	v_mfma_f32_16x16x32_bf16 v[74:77], v[210:213], v[176:179], v[74:77]
	v_mfma_f32_16x16x32_bf16 v[70:73], v[192:195], v[184:187], v[70:73]
	v_mfma_f32_16x16x32_bf16 v[66:69], v[210:213], v[184:187], v[66:69]
	s_setprio 0
	s_mov_b32 m0, s51
	v_lshl_add_u64 v[218:219], s[46:47], 0, v[0:1]
	s_barrier
	ds_read_b128 v[156:159], v147 offset:16384
	ds_read_b128 v[160:163], v147 offset:17408
	ds_read_b128 v[164:167], v147 offset:18432
	ds_read_b128 v[168:171], v147 offset:19456
	ds_read_b128 v[172:175], v147 offset:20480
	ds_read_b128 v[176:179], v147 offset:21504
	ds_read_b128 v[180:183], v147 offset:22528
	ds_read_b128 v[184:187], v147 offset:23552
	global_load_lds_dwordx4 v[218:219], off
	v_lshl_add_u64 v[220:221], s[46:47], 0, v[130:131]
	s_mov_b32 m0, s52
	s_nop 0
	global_load_lds_dwordx4 v[220:221], off
	s_waitcnt vmcnt(10)
	s_barrier
	s_waitcnt lgkmcnt(0)
	s_setprio 1
	s_waitcnt lgkmcnt(0)
	v_mfma_f32_16x16x32_bf16 v[62:65], v[136:139], v[156:159], v[62:65]
	v_mfma_f32_16x16x32_bf16 v[58:61], v[148:151], v[156:159], v[58:61]
	v_mfma_f32_16x16x32_bf16 v[54:57], v[136:139], v[164:167], v[54:57]
	v_mfma_f32_16x16x32_bf16 v[50:53], v[148:151], v[164:167], v[50:53]
	v_mfma_f32_16x16x32_bf16 v[30:33], v[136:139], v[172:175], v[30:33]
	v_mfma_f32_16x16x32_bf16 v[26:29], v[148:151], v[172:175], v[26:29]
	v_mfma_f32_16x16x32_bf16 v[22:25], v[136:139], v[180:183], v[22:25]
	v_mfma_f32_16x16x32_bf16 v[18:21], v[148:151], v[180:183], v[18:21]
	v_mfma_f32_16x16x32_bf16 v[62:65], v[140:143], v[160:163], v[62:65]
	v_mfma_f32_16x16x32_bf16 v[58:61], v[152:155], v[160:163], v[58:61]
	v_mfma_f32_16x16x32_bf16 v[54:57], v[140:143], v[168:171], v[54:57]
	v_mfma_f32_16x16x32_bf16 v[50:53], v[152:155], v[168:171], v[50:53]
	v_mfma_f32_16x16x32_bf16 v[30:33], v[140:143], v[176:179], v[30:33]
	v_mfma_f32_16x16x32_bf16 v[26:29], v[152:155], v[176:179], v[26:29]
	v_mfma_f32_16x16x32_bf16 v[22:25], v[140:143], v[184:187], v[22:25]
	v_mfma_f32_16x16x32_bf16 v[18:21], v[152:155], v[184:187], v[18:21]
	s_setprio 0
	s_barrier
; #define PG8_STAGE(bufoff, gbase, voff) do { _Pragma("unroll") for (int _i = 0; _i < 2; ++_i) \
;         __builtin_amdgcn_global_load_lds((const unsigned*)((const char*)(gbase) + (voff)[_i]), (LAS unsigned*)(lds + (bufoff) + ldsw + _i * 8192), 16, 0, 0); } while (0)
; #define PG8_LDA(dst, b, h) do { _Pragma("unroll") for (int m = 0; m < 4; ++m) _Pragma("unroll") for (int k = 0; k < 2; ++k) dst[m][k] = *(const LAS bf16x8*)(lds + PG8_SA(b, h) + aoff + m * 2048 + k * 1024); } while (0)
; #define PG8_LDB(dst, b, h) do { _Pragma("unroll") for (int n = 0; n < 2; ++n) _Pragma("unroll") for (int k = 0; k < 2; ++k) dst[n][k] = *(const LAS bf16x8*)(lds + PG8_SB(b, h) + boff + n * 2048 + k * 1024); } while (0)
; #define PG8_MMA(ai, bj, At, Bt) do { __builtin_amdgcn_s_setprio(1); _Pragma("unroll") for (int m = 0; m < 4; ++m) _Pragma("unroll") for (int n = 0; n < 2; ++n) _Pragma("unroll") for (int k = 0; k < 2; ++k) \
;         acc[ai][bj][m][n] = __builtin_amdgcn_mfma_f32_16x16x32_bf16(Bt[n][k], At[m][k], acc[ai][bj][m][n], 0, 0, 0); __builtin_amdgcn_s_setprio(0); } while (0)
; #define PG8_WAIT_V(n) asm volatile("s_waitcnt vmcnt(" #n ")" ::: "memory")
; #define PG8_WAIT_L(n) asm volatile("s_waitcnt lgkmcnt(" #n ")" ::: "memory")
; #define PG8_BAR __builtin_amdgcn_s_barrier()
; #define PG8_SCHED __builtin_amdgcn_sched_barrier(0)
; #define PG8_LDA(dst, b, h) do { _Pragma("unroll") for (int m = 0; m < 4; ++m) _Pragma("unroll") for (int k = 0; k < 2; ++k) dst[m][k] = *(const LAS bf16x8*)(lds + PG8_SA(b, h) + aoff + m * 2048 + k * 1024); } while (0)
; #define PG8_WAIT_V(n) asm volatile("s_waitcnt vmcnt(" #n ")" ::: "memory")
; template <class Epi, class Sched>
; DI void gemm_phase(LAS unsigned char* lds, const Gemm g, const Sched& S, const Epi& E) {
;     ...
;             PG8_STAGE(PG8_SB(0, 1), b2 + hstepB, voffB);
;             PG8_WAIT_V(6); PG8_BAR; PG8_MMA(1, 1, At, B1); PG8_BAR;
;             PG8_LDB(B0, 1, 0); PG8_SCHED; PG8_LDA(At, 1, 0); PG8_STAGE(PG8_SA(0, 1), a2 + hstepA, voffA);
;             PG8_WAIT_L(8); PG8_BAR; PG8_WAIT_L(0); PG8_MMA(0, 0, At, B0); PG8_BAR; PG8_SCHED;
;             PG8_LDB(B1, 1, 1); PG8_STAGE(PG8_SB(1, 0), b3, voffB);
;             PG8_BAR; PG8_WAIT_L(0); PG8_MMA(0, 1, At, B1); PG8_BAR;
;             PG8_LDA(At, 1, 1); PG8_STAGE(PG8_SA(1, 0), a3, voffA);
;             PG8_BAR; PG8_WAIT_L(0); PG8_MMA(1, 0, At, B0); PG8_BAR; PG8_SCHED;
	s_add_u32 s0, s44, 0x40000
	s_addc_u32 s1, s45, 0
	s_add_i32 s11, s61, s50
	v_lshl_add_u64 v[136:137], s[0:1], 0, v[0:1]
	s_mov_b32 m0, s11
	s_nop 0
	global_load_lds_dwordx4 v[136:137], off
	v_lshl_add_u64 v[136:137], s[0:1], 0, v[130:131]
	s_add_i32 m0, s11, 0x2000
	s_nop 0
	global_load_lds_dwordx4 v[136:137], off
	v_add_u32_e32 v152, 0x18000, v145
	ds_read_b128 v[136:139], v152
	ds_read_b128 v[140:143], v152 offset:1024
	ds_read_b128 v[148:151], v152 offset:2048
	ds_read_b128 v[152:155], v152 offset:3072
	s_waitcnt vmcnt(6)
	s_barrier
	s_setprio 1
	v_mfma_f32_16x16x32_bf16 v[46:49], v[188:191], v[156:159], v[46:49]
	v_mfma_f32_16x16x32_bf16 v[42:45], v[196:199], v[156:159], v[42:45]
	v_mfma_f32_16x16x32_bf16 v[38:41], v[188:191], v[164:167], v[38:41]
	v_mfma_f32_16x16x32_bf16 v[34:37], v[196:199], v[164:167], v[34:37]
	v_mfma_f32_16x16x32_bf16 v[14:17], v[188:191], v[172:175], v[14:17]
	v_mfma_f32_16x16x32_bf16 v[10:13], v[196:199], v[172:175], v[10:13]
	v_mfma_f32_16x16x32_bf16 v[6:9], v[188:191], v[180:183], v[6:9]
	v_mfma_f32_16x16x32_bf16 v[2:5], v[196:199], v[180:183], v[2:5]
	v_mfma_f32_16x16x32_bf16 v[46:49], v[192:195], v[160:163], v[46:49]
	v_mfma_f32_16x16x32_bf16 v[42:45], v[210:213], v[160:163], v[42:45]
	v_mfma_f32_16x16x32_bf16 v[38:41], v[192:195], v[168:171], v[38:41]
	v_mfma_f32_16x16x32_bf16 v[34:37], v[210:213], v[168:171], v[34:37]
	v_mfma_f32_16x16x32_bf16 v[14:17], v[192:195], v[176:179], v[14:17]
	v_mfma_f32_16x16x32_bf16 v[10:13], v[210:213], v[176:179], v[10:13]
	v_mfma_f32_16x16x32_bf16 v[6:9], v[192:195], v[184:187], v[6:9]
	v_mfma_f32_16x16x32_bf16 v[2:5], v[210:213], v[184:187], v[2:5]
	s_setprio 0
	s_add_i32 s11, 0, 0x18000
	s_barrier
	s_add_u32 s0, s46, 0x40000
	s_addc_u32 s1, s47, 0
	s_mov_b32 m0, s53
	v_lshl_add_u64 v[188:189], s[0:1], 0, v[0:1]
	ds_read_b128 v[156:159], v147 offset:32768
	ds_read_b128 v[160:163], v147 offset:33792
	ds_read_b128 v[164:167], v147 offset:34816
	ds_read_b128 v[168:171], v147 offset:35840
	ds_read_b128 v[172:175], v147 offset:36864
	ds_read_b128 v[176:179], v147 offset:37888
	ds_read_b128 v[180:183], v147 offset:38912
	ds_read_b128 v[184:187], v147 offset:39936
	global_load_lds_dwordx4 v[188:189], off
	v_lshl_add_u64 v[188:189], s[0:1], 0, v[130:131]
	s_mov_b32 m0, s54
	s_nop 0
	global_load_lds_dwordx4 v[188:189], off
	s_waitcnt lgkmcnt(8)
	s_barrier
	s_waitcnt lgkmcnt(0)
	s_setprio 1
	s_waitcnt lgkmcnt(0)
	v_mfma_f32_16x16x32_bf16 v[126:129], v[136:139], v[156:159], v[126:129]
	v_mfma_f32_16x16x32_bf16 v[122:125], v[148:151], v[156:159], v[122:125]
	v_mfma_f32_16x16x32_bf16 v[118:121], v[136:139], v[164:167], v[118:121]
	v_mfma_f32_16x16x32_bf16 v[114:117], v[148:151], v[164:167], v[114:117]
	v_mfma_f32_16x16x32_bf16 v[94:97], v[136:139], v[172:175], v[94:97]
	v_mfma_f32_16x16x32_bf16 v[90:93], v[148:151], v[172:175], v[90:93]
	v_mfma_f32_16x16x32_bf16 v[86:89], v[136:139], v[180:183], v[86:89]
	v_mfma_f32_16x16x32_bf16 v[82:85], v[148:151], v[180:183], v[82:85]
	v_mfma_f32_16x16x32_bf16 v[126:129], v[140:143], v[160:163], v[126:129]
	v_mfma_f32_16x16x32_bf16 v[122:125], v[152:155], v[160:163], v[122:125]
	v_mfma_f32_16x16x32_bf16 v[118:121], v[140:143], v[168:171], v[118:121]
	v_mfma_f32_16x16x32_bf16 v[114:117], v[152:155], v[168:171], v[114:117]
	v_mfma_f32_16x16x32_bf16 v[94:97], v[140:143], v[176:179], v[94:97]
	v_mfma_f32_16x16x32_bf16 v[90:93], v[152:155], v[176:179], v[90:93]
	v_mfma_f32_16x16x32_bf16 v[86:89], v[140:143], v[184:187], v[86:89]
	v_mfma_f32_16x16x32_bf16 v[82:85], v[152:155], v[184:187], v[82:85]
	s_setprio 0
	s_barrier
	s_add_i32 s46, 0, 0x1c000
	s_add_i32 s0, s11, s50
	v_add_u32_e32 v210, s46, v145
	v_lshl_add_u64 v[214:215], v[214:215], 0, s[16:17]
	s_mov_b32 m0, s0
	ds_read_b128 v[188:191], v210
	ds_read_b128 v[192:195], v210 offset:1024
	ds_read_b128 v[196:199], v210 offset:2048
	ds_read_b128 v[210:213], v210 offset:3072
	global_load_lds_dwordx4 v[214:215], off
	v_lshl_add_u64 v[214:215], v[216:217], 0, s[16:17]
	s_add_i32 m0, s0, 0x2000
	s_nop 0
	global_load_lds_dwordx4 v[214:215], off
	s_barrier
; #define PG8_STAGE(bufoff, gbase, voff) do { _Pragma("unroll") for (int _i = 0; _i < 2; ++_i) \
;         __builtin_amdgcn_global_load_lds((const unsigned*)((const char*)(gbase) + (voff)[_i]), (LAS unsigned*)(lds + (bufoff) + ldsw + _i * 8192), 16, 0, 0); } while (0)
; #define PG8_LDA(dst, b, h) do { _Pragma("unroll") for (int m = 0; m < 4; ++m) _Pragma("unroll") for (int k = 0; k < 2; ++k) dst[m][k] = *(const LAS bf16x8*)(lds + PG8_SA(b, h) + aoff + m * 2048 + k * 1024); } while (0)
; #define PG8_MMA(ai, bj, At, Bt) do { __builtin_amdgcn_s_setprio(1); _Pragma("unroll") for (int m = 0; m < 4; ++m) _Pragma("unroll") for (int n = 0; n < 2; ++n) _Pragma("unroll") for (int k = 0; k < 2; ++k) \
;         acc[ai][bj][m][n] = __builtin_amdgcn_mfma_f32_16x16x32_bf16(Bt[n][k], At[m][k], acc[ai][bj][m][n], 0, 0, 0); __builtin_amdgcn_s_setprio(0); } while (0)
; #define PG8_WAIT_V(n) asm volatile("s_waitcnt vmcnt(" #n ")" ::: "memory")
; #define PG8_WAIT_L(n) asm volatile("s_waitcnt lgkmcnt(" #n ")" ::: "memory")
; #define PG8_BAR __builtin_amdgcn_s_barrier()
; #define PG8_SCHED __builtin_amdgcn_sched_barrier(0)
; #define PG8_LDA(dst, b, h) do { _Pragma("unroll") for (int m = 0; m < 4; ++m) _Pragma("unroll") for (int k = 0; k < 2; ++k) dst[m][k] = *(const LAS bf16x8*)(lds + PG8_SA(b, h) + aoff + m * 2048 + k * 1024); } while (0)
; #define PG8_MMA(ai, bj, At, Bt) do { __builtin_amdgcn_s_setprio(1); _Pragma("unroll") for (int m = 0; m < 4; ++m) _Pragma("unroll") for (int n = 0; n < 2; ++n) _Pragma("unroll") for (int k = 0; k < 2; ++k)         acc[ai][bj][m][n] = __builtin_amdgcn_mfma_f32_16x16x32_bf16(Bt[n][k], At[m][k], acc[ai][bj][m][n], 0, 0, 0); __builtin_amdgcn_s_setprio(0); } while (0)
; #define PG8_WAIT_V(n) asm volatile("s_waitcnt vmcnt(" #n ")" ::: "memory")
; template <class Epi, class Sched>
; DI void gemm_phase(LAS unsigned char* lds, const Gemm g, const Sched& S, const Epi& E) {
;     ...
;             PG8_BAR; PG8_WAIT_L(0); PG8_MMA(0, 1, At, B1); PG8_BAR;
;             PG8_LDA(At, 1, 1); PG8_STAGE(PG8_SA(1, 0), a3, voffA);
;             PG8_BAR; PG8_WAIT_L(0); PG8_MMA(1, 0, At, B0); PG8_BAR; PG8_SCHED;
;             PG8_STAGE(PG8_SB(1, 1), b3 + hstepB, voffB);
;             PG8_WAIT_V(6); PG8_BAR; PG8_MMA(1, 1, At, B1); PG8_BAR;
;         }
;         if constexpr (!Epi::AFTER_DRAIN) { E(acc, cur, wr, wc, fr, fq); S.done(cur); }
	s_waitcnt lgkmcnt(0)
	s_setprio 1
	s_waitcnt lgkmcnt(0)
	v_mfma_f32_16x16x32_bf16 v[110:113], v[188:191], v[156:159], v[110:113]
	v_mfma_f32_16x16x32_bf16 v[106:109], v[196:199], v[156:159], v[106:109]
	v_mfma_f32_16x16x32_bf16 v[102:105], v[188:191], v[164:167], v[102:105]
	v_mfma_f32_16x16x32_bf16 v[98:101], v[196:199], v[164:167], v[98:101]
	v_mfma_f32_16x16x32_bf16 v[78:81], v[188:191], v[172:175], v[78:81]
	v_mfma_f32_16x16x32_bf16 v[74:77], v[196:199], v[172:175], v[74:77]
	v_mfma_f32_16x16x32_bf16 v[70:73], v[188:191], v[180:183], v[70:73]
	v_mfma_f32_16x16x32_bf16 v[66:69], v[196:199], v[180:183], v[66:69]
	v_mfma_f32_16x16x32_bf16 v[110:113], v[192:195], v[160:163], v[110:113]
	v_mfma_f32_16x16x32_bf16 v[106:109], v[210:213], v[160:163], v[106:109]
	v_mfma_f32_16x16x32_bf16 v[102:105], v[192:195], v[168:171], v[102:105]
	v_mfma_f32_16x16x32_bf16 v[98:101], v[210:213], v[168:171], v[98:101]
	v_mfma_f32_16x16x32_bf16 v[78:81], v[192:195], v[176:179], v[78:81]
	v_mfma_f32_16x16x32_bf16 v[74:77], v[210:213], v[176:179], v[74:77]
	v_mfma_f32_16x16x32_bf16 v[70:73], v[192:195], v[184:187], v[70:73]
	v_mfma_f32_16x16x32_bf16 v[66:69], v[210:213], v[184:187], v[66:69]
	s_setprio 0
	s_mov_b32 m0, s55
	v_lshl_add_u64 v[214:215], v[218:219], 0, s[16:17]
	s_barrier
	ds_read_b128 v[156:159], v147 offset:49152
	ds_read_b128 v[160:163], v147 offset:50176
	ds_read_b128 v[164:167], v147 offset:51200
	ds_read_b128 v[168:171], v147 offset:52224
	ds_read_b128 v[172:175], v147 offset:53248
	ds_read_b128 v[176:179], v147 offset:54272
	ds_read_b128 v[180:183], v147 offset:55296
	ds_read_b128 v[184:187], v147 offset:56320
	global_load_lds_dwordx4 v[214:215], off
	v_lshl_add_u64 v[214:215], v[220:221], 0, s[16:17]
	s_mov_b32 m0, s56
	s_nop 0
	global_load_lds_dwordx4 v[214:215], off
	s_waitcnt vmcnt(10)
	s_barrier
	s_waitcnt lgkmcnt(0)
	s_setprio 1
	s_waitcnt lgkmcnt(0)
	v_mfma_f32_16x16x32_bf16 v[62:65], v[136:139], v[156:159], v[62:65]
	v_mfma_f32_16x16x32_bf16 v[58:61], v[148:151], v[156:159], v[58:61]
	v_mfma_f32_16x16x32_bf16 v[54:57], v[136:139], v[164:167], v[54:57]
	v_mfma_f32_16x16x32_bf16 v[50:53], v[148:151], v[164:167], v[50:53]
	v_mfma_f32_16x16x32_bf16 v[30:33], v[136:139], v[172:175], v[30:33]
	v_mfma_f32_16x16x32_bf16 v[26:29], v[148:151], v[172:175], v[26:29]
	v_mfma_f32_16x16x32_bf16 v[22:25], v[136:139], v[180:183], v[22:25]
	v_mfma_f32_16x16x32_bf16 v[18:21], v[148:151], v[180:183], v[18:21]
	v_mfma_f32_16x16x32_bf16 v[62:65], v[140:143], v[160:163], v[62:65]
	v_mfma_f32_16x16x32_bf16 v[58:61], v[152:155], v[160:163], v[58:61]
	v_mfma_f32_16x16x32_bf16 v[54:57], v[140:143], v[168:171], v[54:57]
	v_mfma_f32_16x16x32_bf16 v[50:53], v[152:155], v[168:171], v[50:53]
	v_mfma_f32_16x16x32_bf16 v[30:33], v[140:143], v[176:179], v[30:33]
	v_mfma_f32_16x16x32_bf16 v[26:29], v[152:155], v[176:179], v[26:29]
	v_mfma_f32_16x16x32_bf16 v[22:25], v[140:143], v[184:187], v[22:25]
	v_mfma_f32_16x16x32_bf16 v[18:21], v[152:155], v[184:187], v[18:21]
	s_setprio 0
	s_barrier
	s_add_u32 s0, s44, 0x40080
	s_addc_u32 s1, s45, 0
	s_add_i32 s11, s46, s50
	v_lshl_add_u64 v[136:137], s[0:1], 0, v[0:1]
	s_mov_b32 m0, s11
	s_nop 0
	global_load_lds_dwordx4 v[136:137], off
	v_lshl_add_u64 v[136:137], s[0:1], 0, v[130:131]
	s_add_i32 m0, s11, 0x2000
	s_nop 0
	global_load_lds_dwordx4 v[136:137], off
	v_add_u32_e32 v152, 0x10000, v145
	ds_read_b128 v[136:139], v152
	ds_read_b128 v[140:143], v152 offset:1024
	ds_read_b128 v[148:151], v152 offset:2048
	ds_read_b128 v[152:155], v152 offset:3072
	s_waitcnt vmcnt(6)
	s_barrier
	s_setprio 1
	v_mfma_f32_16x16x32_bf16 v[46:49], v[188:191], v[156:159], v[46:49]
	v_mfma_f32_16x16x32_bf16 v[42:45], v[196:199], v[156:159], v[42:45]
	v_mfma_f32_16x16x32_bf16 v[38:41], v[188:191], v[164:167], v[38:41]
	v_mfma_f32_16x16x32_bf16 v[34:37], v[196:199], v[164:167], v[34:37]
	v_mfma_f32_16x16x32_bf16 v[14:17], v[188:191], v[172:175], v[14:17]
	v_mfma_f32_16x16x32_bf16 v[10:13], v[196:199], v[172:175], v[10:13]
	v_mfma_f32_16x16x32_bf16 v[6:9], v[188:191], v[180:183], v[6:9]
	v_mfma_f32_16x16x32_bf16 v[2:5], v[196:199], v[180:183], v[2:5]
	v_mfma_f32_16x16x32_bf16 v[46:49], v[192:195], v[160:163], v[46:49]
	v_mfma_f32_16x16x32_bf16 v[42:45], v[210:213], v[160:163], v[42:45]
	v_mfma_f32_16x16x32_bf16 v[38:41], v[192:195], v[168:171], v[38:41]
	v_mfma_f32_16x16x32_bf16 v[34:37], v[210:213], v[168:171], v[34:37]
	v_mfma_f32_16x16x32_bf16 v[14:17], v[192:195], v[176:179], v[14:17]
	v_mfma_f32_16x16x32_bf16 v[10:13], v[210:213], v[176:179], v[10:13]
	v_mfma_f32_16x16x32_bf16 v[6:9], v[192:195], v[184:187], v[6:9]
	v_mfma_f32_16x16x32_bf16 v[2:5], v[210:213], v[184:187], v[2:5]
	s_setprio 0
	s_add_i32 s60, s60, 2
	s_add_u32 s58, s58, 0x100
	s_addc_u32 s59, s59, 0
	s_add_u32 s42, s42, 0x100
	s_addc_u32 s43, s43, 0
	s_cmp_gt_u32 s60, 13
	s_barrier
	s_cbranch_scc0 .LBB0_1039
	s_waitcnt lgkmcnt(0)
	s_cmp_eq_u64 s[2:3], s[4:5]
	s_cbranch_scc1 .Lfz_p1
	s_branch .Lfz_p1b

; DI float wave_sum_fast(float v) { v = fdpp_add(v, 0); v = fdpp_add(v, 1); v = fdpp_add(v, 2); v = fdpp_add(v, 3); v = xor16_sum(v); return xor32_sum(v); }
; DI void rmsnorm_rows(const float* x, const float* g, bf16_t* outb, float* outf) {
;     ...
;     for (int rr = 0; rr < 2; ++rr) {
; #pragma unroll
;       for (int i = 0; i < 4; ++i) ss[rr] += v[rr][i].x * v[rr][i].x + v[rr][i].y * v[rr][i].y + v[rr][i].z * v[rr][i].z + v[rr][i].w * v[rr][i].w;
;       ss[rr] = wave_sum_fast(ss[rr]);
;     }
.LBB0_1044:
	s_cmp_lg_u32 s92, 0
	s_cbranch_scc0 .Lfz_nox
	v_lshrrev_b32_e32 v191, 6, v201
	v_lshrrev_b32_e32 v192, 2, v191
	v_and_b32_e32 v193, 3, v191
	v_and_b32_e32 v194, 15, v201
	v_bfe_u32 v195, v201, 4, 2
	v_lshl_or_b32 v196, v192, 6, v194
	v_lshl_or_b32 v197, v193, 2, v195
	v_lshlrev_b32_e32 v196, 6, v196
	v_lshl_add_u32 v196, v197, 2, v196
	v_add_u32_e32 v196, 0x20000, v196
	ds_write_b32 v196, v182
	ds_write_b32 v196, v183 offset:1024
	ds_write_b32 v196, v184 offset:2048
	ds_write_b32 v196, v185 offset:3072
	ds_write_b32 v196, v186 offset:8192
	ds_write_b32 v196, v187 offset:9216
	ds_write_b32 v196, v188 offset:10240
	ds_write_b32 v196, v189 offset:11264
	v_readlane_b32 s94, v252, 6
	v_readlane_b32 s95, v252, 7
	s_load_dwordx2 s[94:95], s[94:95], 0xf0
	s_waitcnt lgkmcnt(0)
	s_barrier
	v_cmp_gt_u32_e32 vcc, 0x100, v201
	s_and_saveexec_b64 s[96:97], vcc
	v_lshlrev_b32_e32 v197, 6, v201
	v_add_u32_e32 v197, 0x20000, v197
	ds_read_b128 v[150:153], v197
	ds_read_b128 v[154:157], v197 offset:16
	ds_read_b128 v[158:161], v197 offset:32
	ds_read_b128 v[162:165], v197 offset:48
	s_lshl_b32 s93, s91, 16
	s_lshl_b32 s88, s90, 10
	s_add_u32 s93, s93, s88
	s_add_u32 s94, s94, 0xaaa4500
	s_addc_u32 s95, s95, 0
	s_add_u32 s94, s94, s93
	s_addc_u32 s95, s95, 0
	v_lshlrev_b32_e32 v198, 2, v201
	s_waitcnt lgkmcnt(0)
	v_add_f32_e32 v150, v150, v151
	v_add_f32_e32 v150, v150, v152
	v_add_f32_e32 v150, v150, v153
	v_add_f32_e32 v150, v150, v154
	v_add_f32_e32 v150, v150, v155
	v_add_f32_e32 v150, v150, v156
	v_add_f32_e32 v150, v150, v157
	v_add_f32_e32 v150, v150, v158
	v_add_f32_e32 v150, v150, v159
	v_add_f32_e32 v150, v150, v160
	v_add_f32_e32 v150, v150, v161
	v_add_f32_e32 v150, v150, v162
	v_add_f32_e32 v150, v150, v163
	v_add_f32_e32 v150, v150, v164
	v_add_f32_e32 v150, v150, v165
	global_store_dword v198, v150, s[94:95]
	s_mov_b64 exec, s[96:97]

; DI float wave_sum_fast(float v) { v = fdpp_add(v, 0); v = fdpp_add(v, 1); v = fdpp_add(v, 2); v = fdpp_add(v, 3); v = xor16_sum(v); return xor32_sum(v); }
; DI void rmsnorm_rows(const float* x, const float* g, bf16_t* outb, float* outf) {
;     ...
;     for (int rr = 0; rr < 2; ++rr) {
; #pragma unroll
;       for (int i = 0; i < 4; ++i) ss[rr] += v[rr][i].x * v[rr][i].x + v[rr][i].y * v[rr][i].y + v[rr][i].z * v[rr][i].z + v[rr][i].w * v[rr][i].w;
;       ss[rr] = wave_sum_fast(ss[rr]);
;   DI void operator()(const f32x4 (&acc)[2][2][4][2], const Unit& u, int wr, int wc, int fr, int fq) const {
;     const int row0 = u.pm * BM + wr * 64 + fr, col0 = u.pn * BM + wc * 32 + 4 * fq;
; #pragma unroll
;     for (int ai = 0; ai < 2; ++ai)
; #pragma unroll
;       for (int mp = 0; mp < 2; ++mp) {
;         f32x4 xv[2][2][2];
; #pragma unroll
;         for (int mm = 0; mm < 2; ++mm)
; #pragma unroll
;           for (int bj = 0; bj < 2; ++bj)
; #pragma unroll
;             for (int n = 0; n < 2; ++n)
;               xv[mm][bj][n] = *(const f32x4*)(X + (size_t)(row0 + ai * HALF + (mp * 2 + mm) * 16) * 1024 + col0 + bj * HALF + n * 16);
; #pragma unroll
;         for (int mm = 0; mm < 2; ++mm)
; #pragma unroll
;           for (int bj = 0; bj < 2; ++bj)
; #pragma unroll
;             for (int n = 0; n < 2; ++n)
;               *(f32x4*)(O + (size_t)(row0 + ai * HALF + (mp * 2 + mm) * 16) * 1024 + col0 + bj * HALF + n * 16) = xv[mm][bj][n] + acc[ai][bj][mp * 2 + mm][n];
;       }
;   }
.Lfz_p1b:
	s_mov_b32 s92, 2
	s_mov_b32 s90, s40
	s_mov_b32 s91, s41
	v_lshrrev_b32_e32 v191, 6, v201
	v_lshrrev_b32_e32 v192, 2, v191
	v_and_b32_e32 v193, 3, v191
	v_and_b32_e32 v194, 15, v201
	v_bfe_u32 v195, v201, 4, 2
	v_lshlrev_b32_e32 v190, 18, v192
	v_lshl_or_b32 v190, v194, 12, v190
	v_lshl_or_b32 v190, v193, 7, v190
	v_lshl_or_b32 v190, v195, 4, v190
	s_lshl_b32 s88, s40, 20
	s_lshl_b32 s93, s41, 10
	s_add_u32 s88, s88, s93
	s_add_u32 s100, s2, s88
	s_addc_u32 s101, s3, 0
	s_add_u32 s98, s4, s88
	s_addc_u32 s99, s5, 0
	s_add_u32 s96, s100, 0x0
	s_addc_u32 s97, s101, 0
	global_load_dwordx4 v[150:153], v190, s[96:97]
	global_load_dwordx4 v[154:157], v190, s[96:97] offset:64
	global_load_dwordx4 v[158:161], v190, s[96:97] offset:512
	global_load_dwordx4 v[162:165], v190, s[96:97] offset:576
	s_add_u32 s96, s100, 0x10000
	s_addc_u32 s97, s101, 0
	global_load_dwordx4 v[166:169], v190, s[96:97]
	global_load_dwordx4 v[170:173], v190, s[96:97] offset:64
	global_load_dwordx4 v[174:177], v190, s[96:97] offset:512
	global_load_dwordx4 v[178:181], v190, s[96:97] offset:576
	s_waitcnt vmcnt(0)
	s_add_u32 s94, s98, 0x0
	s_addc_u32 s95, s99, 0
	v_pk_add_f32 v[126:127], v[126:127], v[150:151]
	v_pk_add_f32 v[128:129], v[128:129], v[152:153]
	global_store_dwordx4 v190, v[126:129], s[94:95]
	v_pk_add_f32 v[122:123], v[122:123], v[154:155]
	v_pk_add_f32 v[124:125], v[124:125], v[156:157]
	global_store_dwordx4 v190, v[122:125], s[94:95] offset:64
	v_pk_add_f32 v[110:111], v[110:111], v[158:159]
	v_pk_add_f32 v[112:113], v[112:113], v[160:161]
	global_store_dwordx4 v190, v[110:113], s[94:95] offset:512
	v_pk_add_f32 v[106:107], v[106:107], v[162:163]
	v_pk_add_f32 v[108:109], v[108:109], v[164:165]
	global_store_dwordx4 v190, v[106:109], s[94:95] offset:576
	s_add_u32 s94, s98, 0x10000
	s_addc_u32 s95, s99, 0
	v_pk_add_f32 v[118:119], v[118:119], v[166:167]
	v_pk_add_f32 v[120:121], v[120:121], v[168:169]
	global_store_dwordx4 v190, v[118:121], s[94:95]
	v_pk_add_f32 v[114:115], v[114:115], v[170:171]
	v_pk_add_f32 v[116:117], v[116:117], v[172:173]
	global_store_dwordx4 v190, v[114:117], s[94:95] offset:64
	v_pk_add_f32 v[102:103], v[102:103], v[174:175]
	v_pk_add_f32 v[104:105], v[104:105], v[176:177]
	global_store_dwordx4 v190, v[102:105], s[94:95] offset:512
	v_pk_add_f32 v[98:99], v[98:99], v[178:179]
	v_pk_add_f32 v[100:101], v[100:101], v[180:181]
	global_store_dwordx4 v190, v[98:101], s[94:95] offset:576
	s_nop 0
	s_add_u32 s96, s100, 0x20000
	s_addc_u32 s97, s101, 0
	global_load_dwordx4 v[150:153], v190, s[96:97]
	global_load_dwordx4 v[154:157], v190, s[96:97] offset:64
	global_load_dwordx4 v[158:161], v190, s[96:97] offset:512
	global_load_dwordx4 v[162:165], v190, s[96:97] offset:576
	s_add_u32 s96, s100, 0x30000
	s_addc_u32 s97, s101, 0
	global_load_dwordx4 v[166:169], v190, s[96:97]
	global_load_dwordx4 v[170:173], v190, s[96:97] offset:64
	global_load_dwordx4 v[174:177], v190, s[96:97] offset:512
	global_load_dwordx4 v[178:181], v190, s[96:97] offset:576
	v_pk_mul_f32 v[196:197], v[126:127], v[126:127]
	v_pk_fma_f32 v[196:197], v[128:129], v[128:129], v[196:197]
	v_pk_fma_f32 v[196:197], v[122:123], v[122:123], v[196:197]
	v_pk_fma_f32 v[196:197], v[124:125], v[124:125], v[196:197]
	v_pk_fma_f32 v[196:197], v[110:111], v[110:111], v[196:197]
	v_pk_fma_f32 v[196:197], v[112:113], v[112:113], v[196:197]
	v_pk_fma_f32 v[196:197], v[106:107], v[106:107], v[196:197]
	v_pk_fma_f32 v[196:197], v[108:109], v[108:109], v[196:197]
	s_nop 0
	v_add_f32_e32 v182, v196, v197
	v_pk_mul_f32 v[196:197], v[118:119], v[118:119]
	v_pk_fma_f32 v[196:197], v[120:121], v[120:121], v[196:197]
	v_pk_fma_f32 v[196:197], v[114:115], v[114:115], v[196:197]
	v_pk_fma_f32 v[196:197], v[116:117], v[116:117], v[196:197]
	v_pk_fma_f32 v[196:197], v[102:103], v[102:103], v[196:197]
	v_pk_fma_f32 v[196:197], v[104:105], v[104:105], v[196:197]
	v_pk_fma_f32 v[196:197], v[98:99], v[98:99], v[196:197]
	v_pk_fma_f32 v[196:197], v[100:101], v[100:101], v[196:197]
	s_nop 0
	v_add_f32_e32 v183, v196, v197
	s_waitcnt vmcnt(0)
	s_add_u32 s94, s98, 0x20000
	s_addc_u32 s95, s99, 0
	v_pk_add_f32 v[94:95], v[94:95], v[150:151]
	v_pk_add_f32 v[96:97], v[96:97], v[152:153]
	global_store_dwordx4 v190, v[94:97], s[94:95]
	v_pk_add_f32 v[90:91], v[90:91], v[154:155]
	v_pk_add_f32 v[92:93], v[92:93], v[156:157]
	global_store_dwordx4 v190, v[90:93], s[94:95] offset:64
	v_pk_add_f32 v[78:79], v[78:79], v[158:159]
	v_pk_add_f32 v[80:81], v[80:81], v[160:161]
	global_store_dwordx4 v190, v[78:81], s[94:95] offset:512
	v_pk_add_f32 v[74:75], v[74:75], v[162:163]
	v_pk_add_f32 v[76:77], v[76:77], v[164:165]
	global_store_dwordx4 v190, v[74:77], s[94:95] offset:576
	s_add_u32 s94, s98, 0x30000
	s_addc_u32 s95, s99, 0
	v_pk_add_f32 v[86:87], v[86:87], v[166:167]
	v_pk_add_f32 v[88:89], v[88:89], v[168:169]
	global_store_dwordx4 v190, v[86:89], s[94:95]
	v_pk_add_f32 v[82:83], v[82:83], v[170:171]
	v_pk_add_f32 v[84:85], v[84:85], v[172:173]
	global_store_dwordx4 v190, v[82:85], s[94:95] offset:64
	v_pk_add_f32 v[70:71], v[70:71], v[174:175]
	v_pk_add_f32 v[72:73], v[72:73], v[176:177]
	global_store_dwordx4 v190, v[70:73], s[94:95] offset:512
	v_pk_add_f32 v[66:67], v[66:67], v[178:179]
	v_pk_add_f32 v[68:69], v[68:69], v[180:181]
	global_store_dwordx4 v190, v[66:69], s[94:95] offset:576
	s_nop 0
	s_add_u32 s96, s100, 0x80000
	s_addc_u32 s97, s101, 0
	global_load_dwordx4 v[150:153], v190, s[96:97]
	global_load_dwordx4 v[154:157], v190, s[96:97] offset:64
	global_load_dwordx4 v[158:161], v190, s[96:97] offset:512
	global_load_dwordx4 v[162:165], v190, s[96:97] offset:576
	s_add_u32 s96, s100, 0x90000
	s_addc_u32 s97, s101, 0
	global_load_dwordx4 v[166:169], v190, s[96:97]
	global_load_dwordx4 v[170:173], v190, s[96:97] offset:64
	global_load_dwordx4 v[174:177], v190, s[96:97] offset:512
	global_load_dwordx4 v[178:181], v190, s[96:97] offset:576
	v_pk_mul_f32 v[196:197], v[94:95], v[94:95]
	v_pk_fma_f32 v[196:197], v[96:97], v[96:97], v[196:197]
	v_pk_fma_f32 v[196:197], v[90:91], v[90:91], v[196:197]
	v_pk_fma_f32 v[196:197], v[92:93], v[92:93], v[196:197]
	v_pk_fma_f32 v[196:197], v[78:79], v[78:79], v[196:197]
	v_pk_fma_f32 v[196:197], v[80:81], v[80:81], v[196:197]
	v_pk_fma_f32 v[196:197], v[74:75], v[74:75], v[196:197]
	v_pk_fma_f32 v[196:197], v[76:77], v[76:77], v[196:197]
	s_nop 0
	v_add_f32_e32 v184, v196, v197
	v_pk_mul_f32 v[196:197], v[86:87], v[86:87]
	v_pk_fma_f32 v[196:197], v[88:89], v[88:89], v[196:197]
	v_pk_fma_f32 v[196:197], v[82:83], v[82:83], v[196:197]
	v_pk_fma_f32 v[196:197], v[84:85], v[84:85], v[196:197]
	v_pk_fma_f32 v[196:197], v[70:71], v[70:71], v[196:197]
	v_pk_fma_f32 v[196:197], v[72:73], v[72:73], v[196:197]
	v_pk_fma_f32 v[196:197], v[66:67], v[66:67], v[196:197]
	v_pk_fma_f32 v[196:197], v[68:69], v[68:69], v[196:197]
	s_nop 0
	v_add_f32_e32 v185, v196, v197
	s_waitcnt vmcnt(0)
; DI float wave_sum_fast(float v) { v = fdpp_add(v, 0); v = fdpp_add(v, 1); v = fdpp_add(v, 2); v = fdpp_add(v, 3); v = xor16_sum(v); return xor32_sum(v); }
; DI void rmsnorm_rows(const float* x, const float* g, bf16_t* outb, float* outf) {
;     ...
;     for (int rr = 0; rr < 2; ++rr) {
; #pragma unroll
;       for (int i = 0; i < 4; ++i) ss[rr] += v[rr][i].x * v[rr][i].x + v[rr][i].y * v[rr][i].y + v[rr][i].z * v[rr][i].z + v[rr][i].w * v[rr][i].w;
;       ss[rr] = wave_sum_fast(ss[rr]);
;   DI void operator()(const f32x4 (&acc)[2][2][4][2], const Unit& u, int wr, int wc, int fr, int fq) const {
;     const int row0 = u.pm * BM + wr * 64 + fr, col0 = u.pn * BM + wc * 32 + 4 * fq;
; #pragma unroll
;     for (int ai = 0; ai < 2; ++ai)
; #pragma unroll
;       for (int mp = 0; mp < 2; ++mp) {
;         f32x4 xv[2][2][2];
; #pragma unroll
;         for (int mm = 0; mm < 2; ++mm)
; #pragma unroll
;           for (int bj = 0; bj < 2; ++bj)
; #pragma unroll
;             for (int n = 0; n < 2; ++n)
;               xv[mm][bj][n] = *(const f32x4*)(X + (size_t)(row0 + ai * HALF + (mp * 2 + mm) * 16) * 1024 + col0 + bj * HALF + n * 16);
; #pragma unroll
;         for (int mm = 0; mm < 2; ++mm)
; #pragma unroll
;           for (int bj = 0; bj < 2; ++bj)
; #pragma unroll
;             for (int n = 0; n < 2; ++n)
;               *(f32x4*)(O + (size_t)(row0 + ai * HALF + (mp * 2 + mm) * 16) * 1024 + col0 + bj * HALF + n * 16) = xv[mm][bj][n] + acc[ai][bj][mp * 2 + mm][n];
;       }
;   }
	s_add_u32 s94, s98, 0x80000
	s_addc_u32 s95, s99, 0
	v_pk_add_f32 v[62:63], v[62:63], v[150:151]
	v_pk_add_f32 v[64:65], v[64:65], v[152:153]
	global_store_dwordx4 v190, v[62:65], s[94:95]
	v_pk_add_f32 v[58:59], v[58:59], v[154:155]
	v_pk_add_f32 v[60:61], v[60:61], v[156:157]
	global_store_dwordx4 v190, v[58:61], s[94:95] offset:64
	v_pk_add_f32 v[46:47], v[46:47], v[158:159]
	v_pk_add_f32 v[48:49], v[48:49], v[160:161]
	global_store_dwordx4 v190, v[46:49], s[94:95] offset:512
	v_pk_add_f32 v[42:43], v[42:43], v[162:163]
	v_pk_add_f32 v[44:45], v[44:45], v[164:165]
	global_store_dwordx4 v190, v[42:45], s[94:95] offset:576
	s_add_u32 s94, s98, 0x90000
	s_addc_u32 s95, s99, 0
	v_pk_add_f32 v[54:55], v[54:55], v[166:167]
	v_pk_add_f32 v[56:57], v[56:57], v[168:169]
	global_store_dwordx4 v190, v[54:57], s[94:95]
	v_pk_add_f32 v[50:51], v[50:51], v[170:171]
	v_pk_add_f32 v[52:53], v[52:53], v[172:173]
	global_store_dwordx4 v190, v[50:53], s[94:95] offset:64
	v_pk_add_f32 v[38:39], v[38:39], v[174:175]
	v_pk_add_f32 v[40:41], v[40:41], v[176:177]
	global_store_dwordx4 v190, v[38:41], s[94:95] offset:512
	v_pk_add_f32 v[34:35], v[34:35], v[178:179]
	v_pk_add_f32 v[36:37], v[36:37], v[180:181]
	global_store_dwordx4 v190, v[34:37], s[94:95] offset:576
	s_nop 0
	s_add_u32 s96, s100, 0xa0000
	s_addc_u32 s97, s101, 0
	global_load_dwordx4 v[150:153], v190, s[96:97]
	global_load_dwordx4 v[154:157], v190, s[96:97] offset:64
	global_load_dwordx4 v[158:161], v190, s[96:97] offset:512
	global_load_dwordx4 v[162:165], v190, s[96:97] offset:576
	s_add_u32 s96, s100, 0xb0000
	s_addc_u32 s97, s101, 0
	global_load_dwordx4 v[166:169], v190, s[96:97]
	global_load_dwordx4 v[170:173], v190, s[96:97] offset:64
	global_load_dwordx4 v[174:177], v190, s[96:97] offset:512
	global_load_dwordx4 v[178:181], v190, s[96:97] offset:576
	v_pk_mul_f32 v[196:197], v[62:63], v[62:63]
	v_pk_fma_f32 v[196:197], v[64:65], v[64:65], v[196:197]
	v_pk_fma_f32 v[196:197], v[58:59], v[58:59], v[196:197]
	v_pk_fma_f32 v[196:197], v[60:61], v[60:61], v[196:197]
	v_pk_fma_f32 v[196:197], v[46:47], v[46:47], v[196:197]
	v_pk_fma_f32 v[196:197], v[48:49], v[48:49], v[196:197]
	v_pk_fma_f32 v[196:197], v[42:43], v[42:43], v[196:197]
	v_pk_fma_f32 v[196:197], v[44:45], v[44:45], v[196:197]
	s_nop 0
	v_add_f32_e32 v186, v196, v197
	v_pk_mul_f32 v[196:197], v[54:55], v[54:55]
	v_pk_fma_f32 v[196:197], v[56:57], v[56:57], v[196:197]
	v_pk_fma_f32 v[196:197], v[50:51], v[50:51], v[196:197]
	v_pk_fma_f32 v[196:197], v[52:53], v[52:53], v[196:197]
	v_pk_fma_f32 v[196:197], v[38:39], v[38:39], v[196:197]
	v_pk_fma_f32 v[196:197], v[40:41], v[40:41], v[196:197]
	v_pk_fma_f32 v[196:197], v[34:35], v[34:35], v[196:197]
	v_pk_fma_f32 v[196:197], v[36:37], v[36:37], v[196:197]
	s_nop 0
	v_add_f32_e32 v187, v196, v197
	s_waitcnt vmcnt(0)
	s_add_u32 s94, s98, 0xa0000
	s_addc_u32 s95, s99, 0
	v_pk_add_f32 v[30:31], v[30:31], v[150:151]
	v_pk_add_f32 v[32:33], v[32:33], v[152:153]
	global_store_dwordx4 v190, v[30:33], s[94:95]
	v_pk_add_f32 v[26:27], v[26:27], v[154:155]
	v_pk_add_f32 v[28:29], v[28:29], v[156:157]
	global_store_dwordx4 v190, v[26:29], s[94:95] offset:64
	v_pk_add_f32 v[14:15], v[14:15], v[158:159]
	v_pk_add_f32 v[16:17], v[16:17], v[160:161]
	global_store_dwordx4 v190, v[14:17], s[94:95] offset:512
	v_pk_add_f32 v[10:11], v[10:11], v[162:163]
	v_pk_add_f32 v[12:13], v[12:13], v[164:165]
	global_store_dwordx4 v190, v[10:13], s[94:95] offset:576
	s_add_u32 s94, s98, 0xb0000
	s_addc_u32 s95, s99, 0
	v_pk_add_f32 v[22:23], v[22:23], v[166:167]
	v_pk_add_f32 v[24:25], v[24:25], v[168:169]
	global_store_dwordx4 v190, v[22:25], s[94:95]
	v_pk_add_f32 v[18:19], v[18:19], v[170:171]
	v_pk_add_f32 v[20:21], v[20:21], v[172:173]
	global_store_dwordx4 v190, v[18:21], s[94:95] offset:64
	v_pk_add_f32 v[6:7], v[6:7], v[174:175]
	v_pk_add_f32 v[8:9], v[8:9], v[176:177]
	global_store_dwordx4 v190, v[6:9], s[94:95] offset:512
	v_pk_add_f32 v[2:3], v[2:3], v[178:179]
	v_pk_add_f32 v[4:5], v[4:5], v[180:181]
	global_store_dwordx4 v190, v[2:5], s[94:95] offset:576
	v_pk_mul_f32 v[196:197], v[30:31], v[30:31]
	v_pk_fma_f32 v[196:197], v[32:33], v[32:33], v[196:197]
	v_pk_fma_f32 v[196:197], v[26:27], v[26:27], v[196:197]
	v_pk_fma_f32 v[196:197], v[28:29], v[28:29], v[196:197]
	v_pk_fma_f32 v[196:197], v[14:15], v[14:15], v[196:197]
	v_pk_fma_f32 v[196:197], v[16:17], v[16:17], v[196:197]
	v_pk_fma_f32 v[196:197], v[10:11], v[10:11], v[196:197]
	v_pk_fma_f32 v[196:197], v[12:13], v[12:13], v[196:197]
	s_nop 0
	v_add_f32_e32 v188, v196, v197
	v_pk_mul_f32 v[196:197], v[22:23], v[22:23]
	v_pk_fma_f32 v[196:197], v[24:25], v[24:25], v[196:197]
	v_pk_fma_f32 v[196:197], v[18:19], v[18:19], v[196:197]
	v_pk_fma_f32 v[196:197], v[20:21], v[20:21], v[196:197]
	v_pk_fma_f32 v[196:197], v[6:7], v[6:7], v[196:197]
	v_pk_fma_f32 v[196:197], v[8:9], v[8:9], v[196:197]
	v_pk_fma_f32 v[196:197], v[2:3], v[2:3], v[196:197]
	v_pk_fma_f32 v[196:197], v[4:5], v[4:5], v[196:197]
	s_nop 0
	v_add_f32_e32 v189, v196, v197
	s_nop 1
	v_mov_b32_e32 v130, v18
	v_mov_b32_e32 v131, v19
	v_mov_b32_e32 v132, v20
	v_mov_b32_e32 v133, v21
	v_mov_b32_e32 v134, v14
	v_mov_b32_e32 v135, v15
	v_mov_b32_e32 v136, v16
	v_mov_b32_e32 v137, v17
	v_mov_b32_e32 v138, v10
	v_mov_b32_e32 v139, v11
	v_mov_b32_e32 v140, v12
	v_mov_b32_e32 v141, v13
	v_mov_b32_e32 v142, v6
	v_mov_b32_e32 v143, v7
	v_mov_b32_e32 v144, v8
	v_mov_b32_e32 v145, v9
	v_mov_b32_e32 v146, v2
	v_mov_b32_e32 v147, v3
	v_mov_b32_e32 v148, v4
	v_mov_b32_e32 v149, v5
	s_and_b64 vcc, exec, s[36:37]
	s_mov_b64 s[42:43], s[38:39]
	s_mov_b64 s[44:45], s[34:35]
	s_branch .Lfz_p1_ret
